# in-proj and FFN-up tile order: the 33rd (sample) row panel joins the last 8-panel group (9 x 44 block) instead of a separate 1 x 44 strip on one XCD; in-proj column rotation 18 for heavy-tile balance
# baseline (speedup 1.0000x reference)
.LBB0_134:
	s_load_dwordx16 s[4:19], s[0:1], 0x70
	s_cmp_lt_i32 s44, 2
	s_cselect_b64 s[0:1], -1, 0
	s_cmp_gt_i32 s45, 1
	s_cselect_b64 s[2:3], -1, 0
	s_waitcnt lgkmcnt(0)
	v_writelane_b32 v254, s4, 28
	s_and_b64 s[0:1], s[0:1], s[2:3]
	s_andn2_b64 vcc, exec, s[0:1]
	v_writelane_b32 v254, s5, 29
	v_writelane_b32 v254, s6, 30
	v_writelane_b32 v254, s7, 31
	v_writelane_b32 v254, s8, 32
	v_writelane_b32 v254, s9, 33
	v_writelane_b32 v254, s10, 34
	v_writelane_b32 v254, s11, 35
	v_writelane_b32 v254, s12, 36
	v_writelane_b32 v254, s13, 37
	v_writelane_b32 v254, s14, 38
	v_writelane_b32 v254, s15, 39
	v_writelane_b32 v254, s16, 40
	v_writelane_b32 v254, s17, 41
	v_writelane_b32 v254, s18, 42
	v_writelane_b32 v254, s19, 43
	v_writelane_b32 v254, s84, 44
	s_mov_b64 s[0:1], s[44:45]
	s_mov_b32 s2, s46
	v_writelane_b32 v254, s85, 45
	v_writelane_b32 v254, s86, 46
	v_writelane_b32 v254, s87, 47
	v_writelane_b32 v254, s88, 48
	v_writelane_b32 v254, s89, 49
	v_writelane_b32 v254, s90, 50
	v_writelane_b32 v254, s91, 51
	v_writelane_b32 v254, s0, 52
	s_nop 1
	v_writelane_b32 v254, s1, 53
	v_writelane_b32 v254, s2, 54
	v_writelane_b32 v254, s3, 55
	v_writelane_b32 v254, s43, 56
	s_cbranch_vccnz .LBB0_671
	s_cmpk_lt_i32 s43, 0x5ac
	s_cselect_b64 s[2:3], -1, 0
	s_cmpk_gt_i32 s43, 0x5ab
	v_readfirstlane_b32 s8, v0
	s_cbranch_scc1 .LBB0_137
	s_ashr_i32 s0, s43, 31
	s_lshr_b32 s0, s0, 29
	s_add_i32 s0, s43, s0
	s_and_b32 s1, s0, -8
	s_sub_i32 s1, s43, s1
	s_mul_i32 s5, s1, 0xb5
	s_add_i32 s5, s5, 4
	s_ashr_i32 s0, s0, 3
	s_mul_i32 s4, s1, 0xb6
	s_cmp_lt_i32 s1, 4
	s_cselect_b32 s1, s4, s5
	s_add_i32 s1, s1, s0
	s_mul_hi_i32 s0, s1, 0x2e8ba2e9
	s_lshr_b32 s4, s0, 31
	s_ashr_i32 s0, s0, 6
	s_add_i32 s0, s0, s4
	s_min_i32 s0, s0, 3
	s_lshl_b32 s4, s0, 3
	s_sub_i32 s5, 33, s4
	s_mulk_i32 s0, 0x160
	s_cmp_eq_u32 s4, 24
	s_cselect_b32 s5, 9, 8
	s_sub_i32 s6, s1, s0
	s_sext_i32_i16 s0, s6
	v_cvt_f32_ubyte0_e32 v2, s5
	v_cvt_f32_i32_e32 v1, s0
	v_rcp_iflag_f32_e32 v3, v2
	s_ashr_i32 s0, s0, 30
	s_or_b32 s7, s0, 1
	v_mul_f32_e32 v3, v1, v3
	v_trunc_f32_e32 v3, v3
	v_fma_f32 v1, -v3, v2, v1
	v_cvt_i32_f32_e32 v3, v3
	v_cmp_ge_f32_e64 s[0:1], |v1|, v2
	s_and_b64 s[0:1], s[0:1], exec
	s_cselect_b32 s0, s7, 0
	v_readfirstlane_b32 s1, v3
	s_add_i32 s1, s1, s0
	s_sext_i32_i16 s0, s1
	s_mul_i32 s1, s1, s5
	s_sub_i32 s1, s6, s1
	s_sext_i32_i16 s1, s1
	s_add_i32 s4, s4, s1
	s_add_i32 s1, s0, -26
	s_add_i32 s0, s0, 18
	s_cmp_gt_i32 s0, 43
	s_cselect_b32 s0, s1, s0

.LBB0_148:
	s_ashr_i32 s1, s1, 3
	s_add_i32 s1, s22, s1
	s_mul_hi_i32 s5, s1, 0x2e8ba2e9
	s_lshr_b32 s20, s5, 31
	s_ashr_i32 s5, s5, 6
	s_add_i32 s5, s5, s20
	s_min_i32 s5, s5, 3
	s_lshl_b32 s21, s5, 3
	s_sub_i32 s20, 33, s21
	s_cmp_eq_u32 s21, 24
	s_cselect_b32 s22, 9, 8
	s_abs_i32 s20, s22
	v_cvt_f32_u32_e32 v2, s20
	s_sub_i32 s24, 0, s20
	s_mulk_i32 s5, 0x160
	s_sub_i32 s1, s1, s5
	v_rcp_iflag_f32_e32 v2, v2
	s_abs_i32 s5, s1
	s_xor_b32 s23, s1, s22
	s_ashr_i32 s23, s23, 31
	v_mul_f32_e32 v2, 0x4f7ffffe, v2
	v_cvt_u32_f32_e32 v2, v2
	s_nop 0
	v_readfirstlane_b32 s25, v2
	s_mul_i32 s24, s24, s25
	s_mul_hi_u32 s24, s25, s24
	s_add_i32 s25, s25, s24
	s_mul_hi_u32 s24, s5, s25
	s_mul_i32 s25, s24, s20
	s_sub_i32 s5, s5, s25
	s_add_i32 s26, s24, 1
	s_sub_i32 s25, s5, s20
	s_cmp_ge_u32 s5, s20
	s_cselect_b32 s24, s26, s24
	s_cselect_b32 s5, s25, s5
	s_add_i32 s25, s24, 1
	s_cmp_ge_u32 s5, s20
	s_cselect_b32 s5, s25, s24
	s_xor_b32 s5, s5, s23
	s_sub_i32 s20, s5, s23
	s_mul_i32 s5, s20, s22
	s_sub_i32 s1, s1, s5
	s_add_i32 s22, s21, s1
	s_add_i32 s5, s20, -26
	s_add_i32 s20, s20, 18
	s_cmp_gt_i32 s20, 43
	s_cselect_b32 s20, s5, s20

.LBB0_1121:
	s_cmp_lt_i32 s44, 7
	s_cselect_b64 s[0:1], -1, 0
	s_cmp_gt_i32 s45, 6
	s_cselect_b64 s[2:3], -1, 0
	s_and_b64 s[0:1], s[0:1], s[2:3]
	s_andn2_b64 vcc, exec, s[0:1]
	s_cbranch_vccnz .LBB0_1204
	v_lshlrev_b32_e32 v1, 2, v0
	s_cmpk_gt_i32 s43, 0x5ab
	v_readfirstlane_b32 s1, v0
	s_cbranch_scc1 .LBB0_1142
	v_lshrrev_b32_e32 v4, 1, v0
	v_and_b32_e32 v13, 24, v4
	v_lshrrev_b32_e32 v4, 5, v0
	s_add_u32 s26, s68, 0x2a000000
	v_lshlrev_b32_e32 v2, 4, v0
	v_and_b32_e32 v3, 32, v0
	v_and_b32_e32 v4, 4, v4
	v_bfe_u32 v5, v0, 2, 2
	s_addc_u32 s27, s69, 0
	v_bfe_u32 v12, v0, 2, 4
	v_bitop3_b32 v10, v2, v3, 48 bitop3:0x6c
	v_and_b32_e32 v11, 64, v0
	v_or3_b32 v4, v4, v5, v13
	v_lshrrev_b32_e32 v5, 3, v0
	v_or_b32_e32 v14, 0x2000, v2
	s_add_u32 s28, s68, 0x4600000
	v_or_b32_e32 v3, v10, v11
	v_and_or_b32 v6, v5, 48, v12
	v_and_or_b32 v5, v5, 32, v4
	v_lshrrev_b32_e32 v2, 7, v14
	s_movk_i32 s0, 0x70
	s_addc_u32 s29, s69, 0
	v_lshl_or_b32 v132, v5, 12, v3
	v_and_or_b32 v5, v2, s0, v12
	s_movk_i32 s0, 0x60
	s_ashr_i32 s31, s43, 31
	v_and_or_b32 v2, v2, s0, v4
	s_lshr_b32 s0, s31, 29
	s_add_i32 s0, s43, s0
	s_and_b32 s2, s0, -8
	s_sub_i32 s2, s43, s2
	s_lshr_b32 s6, s1, 6
	s_mul_i32 s4, s2, 0xb5
	s_lshr_b32 s8, s1, 8
	s_lshl_b32 s30, s6, 10
	s_add_i32 s4, s4, 4
	s_ashr_i32 s0, s0, 3
	s_mul_i32 s3, s2, 0xb6
	s_cmp_lt_i32 s2, 4
	s_cselect_b32 s2, s3, s4
	s_add_i32 s2, s2, s0
	s_mul_hi_i32 s0, s2, 0x2e8ba2e9
	s_lshr_b32 s3, s0, 31
	s_ashr_i32 s0, s0, 6
	s_add_i32 s0, s0, s3
	s_min_i32 s0, s0, 3
	s_lshl_b32 s4, s0, 3
	s_sub_i32 s3, 33, s4
	s_mulk_i32 s0, 0x160
	s_cmp_eq_u32 s4, 24
	s_cselect_b32 s5, 9, 8
	s_sub_i32 s7, s2, s0
	v_lshl_or_b32 v134, v5, 12, v3
	s_sext_i32_i16 s0, s7
	v_cvt_f32_ubyte0_e32 v5, s5
	v_lshl_or_b32 v130, v6, 12, v3
	v_cvt_f32_i32_e32 v4, s0
	v_rcp_iflag_f32_e32 v6, v5
	v_lshl_or_b32 v136, v2, 12, v3
	s_ashr_i32 s0, s0, 30
	s_or_b32 s0, s0, 1
	v_mul_f32_e32 v2, v4, v6
	v_trunc_f32_e32 v2, v2
	v_fma_f32 v3, -v2, v5, v4
	v_cvt_i32_f32_e32 v2, v2
	v_cmp_ge_f32_e64 s[2:3], |v3|, v5
	s_and_b64 s[2:3], s[2:3], exec
	s_cselect_b32 s0, s0, 0
	v_readfirstlane_b32 s2, v2
	s_add_i32 s0, s2, s0
	s_mul_i32 s2, s0, s5
	s_sub_i32 s2, s7, s2
	s_sext_i32_i16 s2, s2
	s_add_i32 s18, s4, s2
	s_ashr_i32 s19, s18, 31
	s_bfe_i64 s[4:5], s[0:1], 0x100000
	s_lshl_b64 s[2:3], s[18:19], 20
	s_lshl_b64 s[4:5], s[4:5], 20
	s_add_u32 s22, s28, s4
	s_addc_u32 s23, s29, s5
	s_add_i32 s19, s30, 0
	s_add_i32 m0, s19, 0x10000
	v_mov_b32_e32 v133, 0
	v_lshrrev_b32_e32 v240, 6, v0
	v_bfe_u32 v241, v0, 3, 3
	v_and_b32_e32 v242, 7, v0
	v_lshrrev_b32_e32 v243, 1, v241
	v_and_b32_e32 v244, 1, v240
	v_lshl_or_b32 v243, v244, 2, v243
	v_xor_b32_e32 v242, v242, v243
	v_lshlrev_b32_e32 v242, 4, v242
	v_lshl_add_u32 v245, v240, 3, v241
	v_lshrrev_b32_e32 v246, 2, v240
	v_lshlrev_b32_e32 v246, 5, v246
	v_lshl_add_u32 v246, v244, 4, v246
	v_lshrrev_b32_e32 v247, 2, v241
	v_lshl_add_u32 v246, v247, 3, v246
	v_bfe_u32 v247, v240, 1, 1
	v_lshl_add_u32 v246, v247, 2, v246
	v_and_b32_e32 v247, 3, v241
	v_add_u32_e32 v246, v246, v247
	v_lshl_add_u32 v130, v245, 12, v242
	v_lshl_add_u32 v132, v246, 12, v242
	v_add_u32_e32 v134, 0x40000, v130
	v_add_u32_e32 v136, 0x40000, v132
	global_load_lds_dwordx4 v132, s[22:23]
	s_add_i32 m0, s19, 0x12000
	s_add_u32 s4, s22, 0x80000
	global_load_lds_dwordx4 v136, s[22:23]
	s_addc_u32 s5, s23, 0
	s_add_i32 m0, s19, 0x14000
	v_mov_b32_e32 v137, v133
	global_load_lds_dwordx4 v132, s[4:5]
	s_add_i32 m0, s19, 0x16000
	s_add_u32 s20, s26, s2
	s_addc_u32 s21, s27, s3
	s_add_i32 s33, s19, 0x2000
	global_load_lds_dwordx4 v136, s[4:5]
	s_mov_b32 m0, s19
	s_add_u32 s2, s20, 0x80000
	global_load_lds_dwordx4 v130, s[20:21]
	s_mov_b32 m0, s33
	s_addc_u32 s3, s21, 0
	s_add_i32 s34, s19, 0x4000
	global_load_lds_dwordx4 v134, s[20:21]
	s_mov_b32 m0, s34
	s_add_i32 s35, s19, 0x6000
	global_load_lds_dwordx4 v130, s[2:3]
	s_mov_b32 m0, s35
	v_mov_b32_e32 v131, v133
	global_load_lds_dwordx4 v134, s[2:3]
	v_mov_b32_e32 v135, v133
	s_cmp_eq_u32 s8, 1
	s_mov_b32 s36, 0
	v_lshl_add_u64 v[8:9], s[22:23], 0, v[132:133]
	v_lshl_add_u64 v[6:7], s[22:23], 0, v[136:137]
	v_lshl_add_u64 v[2:3], s[20:21], 0, v[130:131]
	s_cselect_b64 s[2:3], -1, 0
	s_cmp_lg_u32 s8, 1
	v_lshl_add_u64 v[4:5], s[20:21], 0, v[134:135]
	s_cbranch_scc1 .LBB0_1125
	s_barrier

.LBB0_1133:
	s_ashr_i32 s10, s12, 3
	s_add_i32 s10, s14, s10
	s_mul_hi_i32 s11, s10, 0x2e8ba2e9
	s_lshr_b32 s12, s11, 31
	s_ashr_i32 s11, s11, 6
	s_add_i32 s11, s11, s12
	s_min_i32 s11, s11, 3
	s_lshl_b32 s12, s11, 3
	s_sub_i32 s13, 33, s12
	s_cmp_eq_u32 s12, 24
	s_cselect_b32 s13, 9, 8
	s_abs_i32 s14, s13
	v_cvt_f32_u32_e32 v2, s14
	s_sub_i32 s16, 0, s14
	s_mulk_i32 s11, 0x160
	s_sub_i32 s11, s10, s11
	v_rcp_iflag_f32_e32 v2, v2
	s_abs_i32 s10, s11
	s_xor_b32 s15, s11, s13
	s_ashr_i32 s15, s15, 31
	v_mul_f32_e32 v2, 0x4f7ffffe, v2
	v_cvt_u32_f32_e32 v2, v2
	s_nop 0
	v_readfirstlane_b32 s17, v2
	s_mul_i32 s16, s16, s17
	s_mul_hi_u32 s16, s17, s16
	s_add_i32 s17, s17, s16
	s_mul_hi_u32 s16, s10, s17
	s_mul_i32 s17, s16, s14
	s_sub_i32 s10, s10, s17
	s_add_i32 s24, s16, 1
	s_sub_i32 s17, s10, s14
	s_cmp_ge_u32 s10, s14
	s_cselect_b32 s16, s24, s16
	s_cselect_b32 s10, s17, s10
	s_add_i32 s17, s16, 1
	s_cmp_ge_u32 s10, s14
	s_cselect_b32 s10, s17, s16
	s_xor_b32 s10, s10, s15
	s_sub_i32 s10, s10, s15
	s_mul_i32 s13, s10, s13
	s_sub_i32 s11, s11, s13
	s_add_i32 s12, s12, s11
